# attention key loop head aligned to 64 bytes (+24 B of pad before the loop)
# speedup vs baseline: 1.0172x; 1.0172x over previous
; #define LAS __attribute__((address_space(3)))
; __device__ __forceinline__ void attn_unit2(LAS unsigned char* lds, const bf16_t* __restrict__ Q, const bf16_t* __restrict__ KN, const bf16_t* __restrict__ KPE, ...
;     ...
;     f32x16 oa0 = {}, oa1 = {}, ob0 = {}, ob1 = {};
;     float ma = -1.0e30f, mb = -1.0e30f, la = 0.f, lb = 0.f;
;     for (int t = 0; t < ntiles; ++t) {
;         __builtin_amdgcn_sched_barrier(0);
;         f32x16 sa0 = {}, sa1 = {}, sb0 = {}, sb1 = {};
;         const LAS unsigned char* ka = lds + sc + ka_off;
; #pragma unroll
;         for (int ds = 0; ds < 6; ++ds) {
;             const bf16x8 k0 = *(const LAS bf16x8*)(ka + ds * 32);
;             const bf16x8 k1 = *(const LAS bf16x8*)(ka + 32 * KROW + ds * 32);
;             sa0 = __builtin_amdgcn_mfma_f32_32x32x16_bf16(k0, qa[ds], sa0, 0, 0, 0);
;             sa1 = __builtin_amdgcn_mfma_f32_32x32x16_bf16(k1, qa[ds], sa1, 0, 0, 0);
;             sb0 = __builtin_amdgcn_mfma_f32_32x32x16_bf16(k0, qb[ds], sb0, 0, 0, 0);
;             sb1 = __builtin_amdgcn_mfma_f32_32x32x16_bf16(k1, qb[ds], sb1, 0, 0, 0);
;         }
.Lat_noprio:
	v_mov_b32_e32 v96, 0
	v_mov_b32_e32 v97, 0
	v_mov_b32_e32 v98, 0
	v_mov_b32_e32 v99, 0
	v_mov_b32_e32 v100, 0
	v_mov_b32_e32 v101, 0
	v_mov_b32_e32 v102, 0
	v_mov_b32_e32 v103, 0
	v_mov_b32_e32 v112, 0
	v_mov_b32_e32 v113, 0
	v_mov_b32_e32 v114, 0
	v_mov_b32_e32 v115, 0
	v_mov_b32_e32 v116, 0
	v_mov_b32_e32 v117, 0
	v_mov_b32_e32 v118, 0
	v_mov_b32_e32 v119, 0
	v_sub_u32_e32 v228, 1, v192
	v_mul_u32_u24_e32 v228, 0xffff, v228
	v_and_b32_e32 v240, 0x3f80, v228
	v_mov_b32_e32 v241, 0
	v_mov_b32_e32 v242, 0
	v_mov_b32_e32 v243, 0
	v_and_b32_e32 v244, 0x4480, v228
	v_mov_b32_e32 v245, 0
	v_mov_b32_e32 v246, 0
	v_mov_b32_e32 v247, 0
	v_mov_b32_e32 v194, 0xc4800000
	v_and_b32_e32 v248, 0x4480, v228
	v_mov_b32_e32 v249, 0
	v_mov_b32_e32 v250, 0
	v_mov_b32_e32 v251, 0
	v_mov_b32_e32 v195, 0xc4800000
	v_add3_u32 v224, s34, v183, v128
	ds_read_b128 v[212:215], v224 offset:0
	ds_read_b128 v[216:219], v224 offset:32
	ds_read_b128 v[220:223], v224 offset:64
	v_mfma_f32_32x32x16_bf16 v[64:79], v[240:243], v[244:247], 0
	v_mfma_f32_32x32x16_bf16 v[80:95], v[240:243], v[248:251], 0
	s_waitcnt lgkmcnt(2)
	v_mfma_f32_32x32x16_bf16 v[64:79], v[212:215], v[130:133], v[64:79]
	v_mfma_f32_32x32x16_bf16 v[80:95], v[212:215], v[138:141], v[80:95]
	ds_read_b128 v[212:215], v224 offset:96
	s_waitcnt lgkmcnt(2)
	v_mfma_f32_32x32x16_bf16 v[64:79], v[216:219], v[134:137], v[64:79]
	v_mfma_f32_32x32x16_bf16 v[80:95], v[216:219], v[142:145], v[80:95]
	ds_read_b128 v[216:219], v224 offset:128
	s_waitcnt lgkmcnt(2)
	v_mfma_f32_32x32x16_bf16 v[64:79], v[220:223], v[146:149], v[64:79]
	v_mfma_f32_32x32x16_bf16 v[80:95], v[220:223], v[154:157], v[80:95]
	ds_read_b128 v[220:223], v224 offset:160
	s_waitcnt lgkmcnt(2)
	v_mfma_f32_32x32x16_bf16 v[64:79], v[212:215], v[150:153], v[64:79]
	v_mfma_f32_32x32x16_bf16 v[80:95], v[212:215], v[158:161], v[80:95]
	s_waitcnt lgkmcnt(1)
	v_mfma_f32_32x32x16_bf16 v[64:79], v[216:219], v[162:165], v[64:79]
	v_mfma_f32_32x32x16_bf16 v[80:95], v[216:219], v[170:173], v[80:95]
	s_waitcnt lgkmcnt(0)
	v_mfma_f32_32x32x16_bf16 v[64:79], v[220:223], v[166:169], v[64:79]
	v_mfma_f32_32x32x16_bf16 v[80:95], v[220:223], v[174:177], v[80:95]
	v_add3_u32 v225, s34, v187, v128
	ds_read_b128 v[196:199], v225 offset:13376
	ds_read_b128 v[200:203], v225 offset:17984
	ds_read_b128 v[204:207], v225 offset:13408
	ds_read_b128 v[208:211], v225 offset:18016
	s_nop 7
	s_nop 3
	s_nop 0
	s_nop 0
	s_nop 0
	s_nop 0
	s_nop 0
	s_nop 0
